# v26
# baseline (speedup 1.0000x reference)
.LBB0_714:
	s_add_u32 s26, s6, 0xfffc0080
	s_addc_u32 s27, s7, -1
	s_add_i32 s63, 0, 0x10000
	v_add_u32_e32 v140, s63, v165
	ds_read_b128 v[128:131], v140
	ds_read_b128 v[132:135], v140 offset:1024
	ds_read_b128 v[136:139], v140 offset:2048
	ds_read_b128 v[140:143], v140 offset:3072
	s_cmp_eq_u32 s51, 12
	s_cselect_b32 s29, s21, s27
	s_cselect_b32 s28, s38, s26
	s_cselect_b32 s27, s11, s50
	s_cselect_b32 s26, s39, s46
	v_lshl_add_u64 v[162:163], s[6:7], 0, v[150:151]
	s_add_i32 m0, s56, 0xc000
	ds_read_b128 v[154:157], v167
	ds_read_b128 v[158:161], v167 offset:1024
	ds_read_b128 v[168:171], v167 offset:2048
	ds_read_b128 v[172:175], v167 offset:3072
	ds_read_b128 v[176:179], v167 offset:4096
	ds_read_b128 v[180:183], v167 offset:5120
	ds_read_b128 v[184:187], v167 offset:6144
	ds_read_b128 v[188:191], v167 offset:7168
	global_load_lds_dwordx4 v[162:163], off
	v_lshl_add_u64 v[162:163], s[6:7], 0, v[152:153]
	s_add_i32 m0, s56, 0xe000
	s_nop 0
	global_load_lds_dwordx4 v[162:163], off
	s_waitcnt lgkmcnt(8)
	s_barrier
	s_waitcnt lgkmcnt(0)
	s_setprio 1
	s_waitcnt lgkmcnt(0)
	v_mfma_f32_16x16x32_bf16 v[124:127], v[128:131], v[154:157], v[124:127]
	v_mfma_f32_16x16x32_bf16 v[120:123], v[136:139], v[154:157], v[120:123]
	v_mfma_f32_16x16x32_bf16 v[116:119], v[128:131], v[168:171], v[116:119]
	v_mfma_f32_16x16x32_bf16 v[112:115], v[136:139], v[168:171], v[112:115]
	v_mfma_f32_16x16x32_bf16 v[108:111], v[128:131], v[176:179], v[108:111]
	v_mfma_f32_16x16x32_bf16 v[104:107], v[136:139], v[176:179], v[104:107]
	v_mfma_f32_16x16x32_bf16 v[100:103], v[128:131], v[184:187], v[100:103]
	v_mfma_f32_16x16x32_bf16 v[96:99], v[136:139], v[184:187], v[96:99]
	v_mfma_f32_16x16x32_bf16 v[124:127], v[132:135], v[158:161], v[124:127]
	v_mfma_f32_16x16x32_bf16 v[120:123], v[140:143], v[158:161], v[120:123]
	v_mfma_f32_16x16x32_bf16 v[116:119], v[132:135], v[172:175], v[116:119]
	v_mfma_f32_16x16x32_bf16 v[112:115], v[140:143], v[172:175], v[112:115]
	v_mfma_f32_16x16x32_bf16 v[108:111], v[132:135], v[180:183], v[108:111]
	v_mfma_f32_16x16x32_bf16 v[104:107], v[140:143], v[180:183], v[104:107]
	v_mfma_f32_16x16x32_bf16 v[100:103], v[132:135], v[188:191], v[100:103]
	v_mfma_f32_16x16x32_bf16 v[96:99], v[140:143], v[188:191], v[96:99]
	s_setprio 0
	s_barrier
	s_add_i32 s66, 0, 0x14000
	v_add_u32_e32 v162, s66, v165
	s_add_i32 s63, s63, s55
	ds_read_b128 v[192:195], v162
	ds_read_b128 v[196:199], v162 offset:1024
	ds_read_b128 v[200:203], v162 offset:2048
	ds_read_b128 v[204:207], v162 offset:3072
	v_lshl_add_u64 v[162:163], s[26:27], 0, v[208:209]
	s_mov_b32 m0, s63
	v_lshl_add_u64 v[210:211], s[26:27], 0, v[144:145]
	global_load_lds_dwordx4 v[162:163], off
	s_add_i32 m0, s63, 0x2000
	s_nop 0
	global_load_lds_dwordx4 v[210:211], off
	s_barrier
	s_waitcnt lgkmcnt(0)
	s_setprio 1
	s_waitcnt lgkmcnt(0)
	v_mfma_f32_16x16x32_bf16 v[60:63], v[192:195], v[154:157], v[60:63]
	v_mfma_f32_16x16x32_bf16 v[56:59], v[200:203], v[154:157], v[56:59]
	v_mfma_f32_16x16x32_bf16 v[52:55], v[192:195], v[168:171], v[52:55]
	v_mfma_f32_16x16x32_bf16 v[48:51], v[200:203], v[168:171], v[48:51]
	v_mfma_f32_16x16x32_bf16 v[44:47], v[192:195], v[176:179], v[44:47]
	v_mfma_f32_16x16x32_bf16 v[40:43], v[200:203], v[176:179], v[40:43]
	v_mfma_f32_16x16x32_bf16 v[36:39], v[192:195], v[184:187], v[36:39]
	v_mfma_f32_16x16x32_bf16 v[32:35], v[200:203], v[184:187], v[32:35]
	v_mfma_f32_16x16x32_bf16 v[60:63], v[196:199], v[158:161], v[60:63]
	v_mfma_f32_16x16x32_bf16 v[56:59], v[204:207], v[158:161], v[56:59]
	v_mfma_f32_16x16x32_bf16 v[52:55], v[196:199], v[172:175], v[52:55]
	v_mfma_f32_16x16x32_bf16 v[48:51], v[204:207], v[172:175], v[48:51]
	v_mfma_f32_16x16x32_bf16 v[44:47], v[196:199], v[180:183], v[44:47]
	v_mfma_f32_16x16x32_bf16 v[40:43], v[204:207], v[180:183], v[40:43]
	v_mfma_f32_16x16x32_bf16 v[36:39], v[196:199], v[188:191], v[36:39]
	v_mfma_f32_16x16x32_bf16 v[32:35], v[204:207], v[188:191], v[32:35]
	s_setprio 0
	s_mov_b32 m0, s56
	v_lshl_add_u64 v[214:215], s[28:29], 0, v[148:149]
	s_barrier
	ds_read_b128 v[154:157], v167 offset:16384
	ds_read_b128 v[158:161], v167 offset:17408
	ds_read_b128 v[168:171], v167 offset:18432
	ds_read_b128 v[172:175], v167 offset:19456
	ds_read_b128 v[176:179], v167 offset:20480
	ds_read_b128 v[180:183], v167 offset:21504
	ds_read_b128 v[184:187], v167 offset:22528
	ds_read_b128 v[188:191], v167 offset:23552
	global_load_lds_dwordx4 v[214:215], off
	v_lshl_add_u64 v[216:217], s[28:29], 0, v[146:147]
	s_mov_b32 m0, s57
	s_nop 0
	global_load_lds_dwordx4 v[216:217], off
	s_barrier
	s_waitcnt lgkmcnt(0)
	s_setprio 1
	s_waitcnt lgkmcnt(0)
	v_mfma_f32_16x16x32_bf16 v[92:95], v[128:131], v[154:157], v[92:95]
	v_mfma_f32_16x16x32_bf16 v[88:91], v[136:139], v[154:157], v[88:91]
	v_mfma_f32_16x16x32_bf16 v[84:87], v[128:131], v[168:171], v[84:87]
	v_mfma_f32_16x16x32_bf16 v[80:83], v[136:139], v[168:171], v[80:83]
	v_mfma_f32_16x16x32_bf16 v[76:79], v[128:131], v[176:179], v[76:79]
	v_mfma_f32_16x16x32_bf16 v[72:75], v[136:139], v[176:179], v[72:75]
	v_mfma_f32_16x16x32_bf16 v[68:71], v[128:131], v[184:187], v[68:71]
	v_mfma_f32_16x16x32_bf16 v[64:67], v[136:139], v[184:187], v[64:67]
	v_mfma_f32_16x16x32_bf16 v[92:95], v[132:135], v[158:161], v[92:95]
	v_mfma_f32_16x16x32_bf16 v[88:91], v[140:143], v[158:161], v[88:91]
	v_mfma_f32_16x16x32_bf16 v[84:87], v[132:135], v[172:175], v[84:87]
	v_mfma_f32_16x16x32_bf16 v[80:83], v[140:143], v[172:175], v[80:83]
	v_mfma_f32_16x16x32_bf16 v[76:79], v[132:135], v[180:183], v[76:79]
	v_mfma_f32_16x16x32_bf16 v[72:75], v[140:143], v[180:183], v[72:75]
	v_mfma_f32_16x16x32_bf16 v[68:71], v[132:135], v[188:191], v[68:71]
	v_mfma_f32_16x16x32_bf16 v[64:67], v[140:143], v[188:191], v[64:67]
	s_setprio 0
	s_barrier
	s_add_u32 s64, s26, 0x40000
	s_addc_u32 s65, s27, 0
	s_add_i32 s63, s66, s55
	v_lshl_add_u64 v[128:129], s[64:65], 0, v[208:209]
	s_mov_b32 m0, s63
	s_nop 0
	global_load_lds_dwordx4 v[128:129], off
	v_lshl_add_u64 v[128:129], s[64:65], 0, v[144:145]
	s_add_i32 m0, s63, 0x2000
	s_nop 0
	global_load_lds_dwordx4 v[128:129], off
	s_waitcnt vmcnt(6)
	s_barrier
	s_setprio 1
	v_mfma_f32_16x16x32_bf16 v[28:31], v[192:195], v[154:157], v[28:31]
	v_mfma_f32_16x16x32_bf16 v[24:27], v[200:203], v[154:157], v[24:27]
	v_mfma_f32_16x16x32_bf16 v[20:23], v[192:195], v[168:171], v[20:23]
	v_mfma_f32_16x16x32_bf16 v[16:19], v[200:203], v[168:171], v[16:19]
	v_mfma_f32_16x16x32_bf16 v[12:15], v[192:195], v[176:179], v[12:15]
	v_mfma_f32_16x16x32_bf16 v[8:11], v[200:203], v[176:179], v[8:11]
	v_mfma_f32_16x16x32_bf16 v[4:7], v[192:195], v[184:187], v[4:7]
	v_mfma_f32_16x16x32_bf16 v[0:3], v[200:203], v[184:187], v[0:3]
	v_mfma_f32_16x16x32_bf16 v[28:31], v[196:199], v[158:161], v[28:31]
	v_mfma_f32_16x16x32_bf16 v[24:27], v[204:207], v[158:161], v[24:27]
	v_mfma_f32_16x16x32_bf16 v[20:23], v[196:199], v[172:175], v[20:23]
	v_mfma_f32_16x16x32_bf16 v[16:19], v[204:207], v[172:175], v[16:19]
	v_mfma_f32_16x16x32_bf16 v[12:15], v[196:199], v[180:183], v[12:15]
	v_mfma_f32_16x16x32_bf16 v[8:11], v[204:207], v[180:183], v[8:11]
	v_mfma_f32_16x16x32_bf16 v[4:7], v[196:199], v[188:191], v[4:7]
	v_mfma_f32_16x16x32_bf16 v[0:3], v[204:207], v[188:191], v[0:3]
	s_setprio 0
	s_add_i32 s63, 0, 0x18000
	v_add_u32_e32 v140, s63, v165
	s_barrier
	ds_read_b128 v[128:131], v140
	ds_read_b128 v[132:135], v140 offset:1024
	ds_read_b128 v[136:139], v140 offset:2048
	ds_read_b128 v[140:143], v140 offset:3072
	s_add_u32 s28, s28, 0x40000
	s_addc_u32 s29, s29, 0
	s_mov_b32 m0, s58
	v_lshl_add_u64 v[192:193], s[28:29], 0, v[148:149]
	ds_read_b128 v[154:157], v167 offset:32768
	ds_read_b128 v[158:161], v167 offset:33792
	ds_read_b128 v[168:171], v167 offset:34816
	ds_read_b128 v[172:175], v167 offset:35840
	ds_read_b128 v[176:179], v167 offset:36864
	ds_read_b128 v[180:183], v167 offset:37888
	ds_read_b128 v[184:187], v167 offset:38912
	ds_read_b128 v[188:191], v167 offset:39936
	global_load_lds_dwordx4 v[192:193], off
	v_lshl_add_u64 v[192:193], s[28:29], 0, v[146:147]
	s_mov_b32 m0, s59
	s_nop 0
	global_load_lds_dwordx4 v[192:193], off
	s_waitcnt lgkmcnt(8)
	s_barrier
	s_waitcnt lgkmcnt(0)
	s_setprio 1
	s_waitcnt lgkmcnt(0)
	v_mfma_f32_16x16x32_bf16 v[124:127], v[128:131], v[154:157], v[124:127]
	v_mfma_f32_16x16x32_bf16 v[120:123], v[136:139], v[154:157], v[120:123]
	v_mfma_f32_16x16x32_bf16 v[116:119], v[128:131], v[168:171], v[116:119]
	v_mfma_f32_16x16x32_bf16 v[112:115], v[136:139], v[168:171], v[112:115]
	v_mfma_f32_16x16x32_bf16 v[108:111], v[128:131], v[176:179], v[108:111]
	v_mfma_f32_16x16x32_bf16 v[104:107], v[136:139], v[176:179], v[104:107]
	v_mfma_f32_16x16x32_bf16 v[100:103], v[128:131], v[184:187], v[100:103]
	v_mfma_f32_16x16x32_bf16 v[96:99], v[136:139], v[184:187], v[96:99]
	v_mfma_f32_16x16x32_bf16 v[124:127], v[132:135], v[158:161], v[124:127]
	v_mfma_f32_16x16x32_bf16 v[120:123], v[140:143], v[158:161], v[120:123]
	v_mfma_f32_16x16x32_bf16 v[116:119], v[132:135], v[172:175], v[116:119]
	v_mfma_f32_16x16x32_bf16 v[112:115], v[140:143], v[172:175], v[112:115]
	v_mfma_f32_16x16x32_bf16 v[108:111], v[132:135], v[180:183], v[108:111]
	v_mfma_f32_16x16x32_bf16 v[104:107], v[140:143], v[180:183], v[104:107]
	v_mfma_f32_16x16x32_bf16 v[100:103], v[132:135], v[188:191], v[100:103]
	v_mfma_f32_16x16x32_bf16 v[96:99], v[140:143], v[188:191], v[96:99]
	s_setprio 0
	s_barrier
	s_add_i32 s28, 0, 0x1c000
	s_add_i32 s29, s63, s55
	v_add_u32_e32 v204, s28, v165
	v_lshl_add_u64 v[162:163], v[162:163], 0, s[40:41]
	s_mov_b32 m0, s29
	ds_read_b128 v[192:195], v204
	ds_read_b128 v[196:199], v204 offset:1024
	ds_read_b128 v[200:203], v204 offset:2048
	ds_read_b128 v[204:207], v204 offset:3072
	global_load_lds_dwordx4 v[162:163], off
	v_lshl_add_u64 v[162:163], v[210:211], 0, s[40:41]
	s_add_i32 m0, s29, 0x2000
	s_nop 0
	global_load_lds_dwordx4 v[162:163], off
	s_barrier
	s_waitcnt lgkmcnt(0)
	s_setprio 1
	s_waitcnt lgkmcnt(0)
	v_mfma_f32_16x16x32_bf16 v[60:63], v[192:195], v[154:157], v[60:63]
	v_mfma_f32_16x16x32_bf16 v[56:59], v[200:203], v[154:157], v[56:59]
	v_mfma_f32_16x16x32_bf16 v[52:55], v[192:195], v[168:171], v[52:55]
	v_mfma_f32_16x16x32_bf16 v[48:51], v[200:203], v[168:171], v[48:51]
	v_mfma_f32_16x16x32_bf16 v[44:47], v[192:195], v[176:179], v[44:47]
	v_mfma_f32_16x16x32_bf16 v[40:43], v[200:203], v[176:179], v[40:43]
	v_mfma_f32_16x16x32_bf16 v[36:39], v[192:195], v[184:187], v[36:39]
	v_mfma_f32_16x16x32_bf16 v[32:35], v[200:203], v[184:187], v[32:35]
	v_mfma_f32_16x16x32_bf16 v[60:63], v[196:199], v[158:161], v[60:63]
	v_mfma_f32_16x16x32_bf16 v[56:59], v[204:207], v[158:161], v[56:59]
	v_mfma_f32_16x16x32_bf16 v[52:55], v[196:199], v[172:175], v[52:55]
	v_mfma_f32_16x16x32_bf16 v[48:51], v[204:207], v[172:175], v[48:51]
	v_mfma_f32_16x16x32_bf16 v[44:47], v[196:199], v[180:183], v[44:47]
	v_mfma_f32_16x16x32_bf16 v[40:43], v[204:207], v[180:183], v[40:43]
	v_mfma_f32_16x16x32_bf16 v[36:39], v[196:199], v[188:191], v[36:39]
	v_mfma_f32_16x16x32_bf16 v[32:35], v[204:207], v[188:191], v[32:35]
	s_setprio 0
	s_mov_b32 m0, s60
	v_lshl_add_u64 v[162:163], v[214:215], 0, s[40:41]
	s_barrier
	ds_read_b128 v[154:157], v167 offset:49152
	ds_read_b128 v[158:161], v167 offset:50176
	ds_read_b128 v[168:171], v167 offset:51200
	ds_read_b128 v[172:175], v167 offset:52224
	ds_read_b128 v[176:179], v167 offset:53248
	ds_read_b128 v[180:183], v167 offset:54272
	ds_read_b128 v[184:187], v167 offset:55296
	ds_read_b128 v[188:191], v167 offset:56320
	global_load_lds_dwordx4 v[162:163], off
	v_lshl_add_u64 v[162:163], v[216:217], 0, s[40:41]
	s_mov_b32 m0, s61
	s_nop 0
	global_load_lds_dwordx4 v[162:163], off
	s_barrier
	s_waitcnt lgkmcnt(0)
	s_setprio 1
	s_waitcnt lgkmcnt(0)
	v_mfma_f32_16x16x32_bf16 v[92:95], v[128:131], v[154:157], v[92:95]
	v_mfma_f32_16x16x32_bf16 v[88:91], v[136:139], v[154:157], v[88:91]
	v_mfma_f32_16x16x32_bf16 v[84:87], v[128:131], v[168:171], v[84:87]
	v_mfma_f32_16x16x32_bf16 v[80:83], v[136:139], v[168:171], v[80:83]
	v_mfma_f32_16x16x32_bf16 v[76:79], v[128:131], v[176:179], v[76:79]
	v_mfma_f32_16x16x32_bf16 v[72:75], v[136:139], v[176:179], v[72:75]
	v_mfma_f32_16x16x32_bf16 v[68:71], v[128:131], v[184:187], v[68:71]
	v_mfma_f32_16x16x32_bf16 v[64:67], v[136:139], v[184:187], v[64:67]
	v_mfma_f32_16x16x32_bf16 v[92:95], v[132:135], v[158:161], v[92:95]
	v_mfma_f32_16x16x32_bf16 v[88:91], v[140:143], v[158:161], v[88:91]
	v_mfma_f32_16x16x32_bf16 v[84:87], v[132:135], v[172:175], v[84:87]
	v_mfma_f32_16x16x32_bf16 v[80:83], v[140:143], v[172:175], v[80:83]
	v_mfma_f32_16x16x32_bf16 v[76:79], v[132:135], v[180:183], v[76:79]
	v_mfma_f32_16x16x32_bf16 v[72:75], v[140:143], v[180:183], v[72:75]
	v_mfma_f32_16x16x32_bf16 v[68:71], v[132:135], v[188:191], v[68:71]
	v_mfma_f32_16x16x32_bf16 v[64:67], v[140:143], v[188:191], v[64:67]
	s_setprio 0
	s_barrier
	s_add_u32 s26, s26, 0x40080
	s_addc_u32 s27, s27, 0
	s_add_i32 s28, s28, s55
	v_lshl_add_u64 v[128:129], s[26:27], 0, v[208:209]
	s_mov_b32 m0, s28
	s_nop 0
	global_load_lds_dwordx4 v[128:129], off
	v_lshl_add_u64 v[128:129], s[26:27], 0, v[144:145]
	s_add_i32 m0, s28, 0x2000
	s_nop 0
	global_load_lds_dwordx4 v[128:129], off
	s_waitcnt vmcnt(6)
	s_barrier
	s_setprio 1
	v_mfma_f32_16x16x32_bf16 v[28:31], v[192:195], v[154:157], v[28:31]
	v_mfma_f32_16x16x32_bf16 v[24:27], v[200:203], v[154:157], v[24:27]
	v_mfma_f32_16x16x32_bf16 v[20:23], v[192:195], v[168:171], v[20:23]
	v_mfma_f32_16x16x32_bf16 v[16:19], v[200:203], v[168:171], v[16:19]
	v_mfma_f32_16x16x32_bf16 v[12:15], v[192:195], v[176:179], v[12:15]
	v_mfma_f32_16x16x32_bf16 v[8:11], v[200:203], v[176:179], v[8:11]
	v_mfma_f32_16x16x32_bf16 v[4:7], v[192:195], v[184:187], v[4:7]
	v_mfma_f32_16x16x32_bf16 v[0:3], v[200:203], v[184:187], v[0:3]
	v_mfma_f32_16x16x32_bf16 v[28:31], v[196:199], v[158:161], v[28:31]
	v_mfma_f32_16x16x32_bf16 v[24:27], v[204:207], v[158:161], v[24:27]
	v_mfma_f32_16x16x32_bf16 v[20:23], v[196:199], v[172:175], v[20:23]
	v_mfma_f32_16x16x32_bf16 v[16:19], v[204:207], v[172:175], v[16:19]
	v_mfma_f32_16x16x32_bf16 v[12:15], v[196:199], v[180:183], v[12:15]
	v_mfma_f32_16x16x32_bf16 v[8:11], v[204:207], v[180:183], v[8:11]
	v_mfma_f32_16x16x32_bf16 v[4:7], v[196:199], v[188:191], v[4:7]
	v_mfma_f32_16x16x32_bf16 v[0:3], v[204:207], v[188:191], v[0:3]
	s_setprio 0
	s_add_i32 s51, s51, 2
	s_add_u32 s6, s6, 0x100
	s_addc_u32 s7, s7, 0
	s_add_u32 s46, s46, 0x100
	s_addc_u32 s50, s50, 0
	s_cmp_gt_u32 s51, 13
	s_barrier
	s_cbranch_scc0 .LBB0_714
	v_lshl_or_b32 v158, s34, 8, v166
	v_lshl_add_u32 v159, s35, 8, v164
	s_mov_b32 s34, s10
	s_mov_b32 s35, s20
	s_mov_b64 s[26:27], s[24:25]
	v_mbcnt_lo_u32_b32 v160, -1, 0
	v_mbcnt_hi_u32_b32 v160, -1, v160
	v_and_b32_e32 v157, 7, v160
	v_and_b32_e32 v160, 8, v160
	v_add_u32_e32 v157, v158, v157
	v_lshlrev_b32_e32 v157, 6, v157
	v_lshl_add_u32 v157, v160, 2, v157
	v_add_u32_e32 v161, 0x2000, v157
	global_load_dwordx4 v[128:131], v157, s[18:19]
	global_load_dwordx4 v[132:135], v157, s[18:19] offset:16
	global_load_dwordx4 v[136:139], v161, s[18:19]
	global_load_dwordx4 v[140:143], v161, s[18:19] offset:16
	v_mov_b32_e32 v155, 0x358637bd
	v_lshlrev_b32_e32 v156, 17, v159
	v_lshl_add_u32 v156, v158, 1, v156
	s_waitcnt vmcnt(0)
	v_pk_add_f32 v[128:129], v[128:129], v[130:131]
	v_pk_add_f32 v[132:133], v[132:133], v[134:135]
	v_pk_add_f32 v[128:129], v[128:129], v[132:133]
	s_nop 0
	v_add_f32_e32 v154, v128, v129
	s_nop 1
	v_add_f32_dpp v154, v154, v154 row_ror:8 row_mask:0xf bank_mask:0xf
	s_nop 0
	v_fmamk_f32 v154, v154, 0x3a800000, v155
	v_rsq_f32_e32 v154, v154
	s_nop 1
	v_mov_b32_dpp v168, v154 row_newbcast:0 row_mask:0xf bank_mask:0xf
	v_mov_b32_dpp v169, v154 row_newbcast:1 row_mask:0xf bank_mask:0xf
	v_mov_b32_dpp v170, v154 row_newbcast:2 row_mask:0xf bank_mask:0xf
	v_mov_b32_dpp v171, v154 row_newbcast:3 row_mask:0xf bank_mask:0xf
	v_mov_b32_dpp v172, v154 row_newbcast:4 row_mask:0xf bank_mask:0xf
	v_mov_b32_dpp v173, v154 row_newbcast:5 row_mask:0xf bank_mask:0xf
	v_mov_b32_dpp v174, v154 row_newbcast:6 row_mask:0xf bank_mask:0xf
	v_mov_b32_dpp v175, v154 row_newbcast:7 row_mask:0xf bank_mask:0xf
	v_pk_add_f32 v[136:137], v[136:137], v[138:139]
	v_pk_add_f32 v[140:141], v[140:141], v[142:143]
	v_pk_add_f32 v[136:137], v[136:137], v[140:141]
	s_nop 0
	v_add_f32_e32 v154, v136, v137
	s_nop 1
	v_add_f32_dpp v154, v154, v154 row_ror:8 row_mask:0xf bank_mask:0xf
	s_nop 0
	v_fmamk_f32 v154, v154, 0x3a800000, v155
	v_rsq_f32_e32 v154, v154
	s_nop 1
	v_mov_b32_dpp v176, v154 row_newbcast:0 row_mask:0xf bank_mask:0xf
	v_mov_b32_dpp v177, v154 row_newbcast:1 row_mask:0xf bank_mask:0xf
	v_mov_b32_dpp v178, v154 row_newbcast:2 row_mask:0xf bank_mask:0xf
	v_mov_b32_dpp v179, v154 row_newbcast:3 row_mask:0xf bank_mask:0xf
	v_mov_b32_dpp v180, v154 row_newbcast:4 row_mask:0xf bank_mask:0xf
	v_mov_b32_dpp v181, v154 row_newbcast:5 row_mask:0xf bank_mask:0xf
	v_mov_b32_dpp v182, v154 row_newbcast:6 row_mask:0xf bank_mask:0xf
	v_mov_b32_dpp v183, v154 row_newbcast:7 row_mask:0xf bank_mask:0xf
	v_pk_mul_f32 v[124:125], v[124:125], v[168:169]
	v_pk_mul_f32 v[126:127], v[126:127], v[170:171]
	v_pk_mul_f32 v[120:121], v[120:121], v[172:173]
	v_pk_mul_f32 v[122:123], v[122:123], v[174:175]
	v_cvt_pk_bf16_f32 v184, v124, v125
	v_cvt_pk_bf16_f32 v185, v126, v127
	v_cvt_pk_bf16_f32 v186, v120, v121
	v_cvt_pk_bf16_f32 v187, v122, v123
	global_store_dwordx4 v156, v[184:187], s[8:9]
	v_pk_mul_f32 v[60:61], v[60:61], v[176:177]
	v_pk_mul_f32 v[62:63], v[62:63], v[178:179]
	v_pk_mul_f32 v[56:57], v[56:57], v[180:181]
	v_pk_mul_f32 v[58:59], v[58:59], v[182:183]
	v_cvt_pk_bf16_f32 v188, v60, v61
	v_cvt_pk_bf16_f32 v189, v62, v63
	v_cvt_pk_bf16_f32 v190, v56, v57
	v_cvt_pk_bf16_f32 v191, v58, v59
	global_store_dwordx4 v156, v[188:191], s[8:9] offset:256
	v_add_u32_e32 v156, 0x200000, v156
	v_pk_mul_f32 v[116:117], v[116:117], v[168:169]
	v_pk_mul_f32 v[118:119], v[118:119], v[170:171]
	v_pk_mul_f32 v[112:113], v[112:113], v[172:173]
	v_pk_mul_f32 v[114:115], v[114:115], v[174:175]
	v_cvt_pk_bf16_f32 v184, v116, v117
	v_cvt_pk_bf16_f32 v185, v118, v119
	v_cvt_pk_bf16_f32 v186, v112, v113
	v_cvt_pk_bf16_f32 v187, v114, v115
	global_store_dwordx4 v156, v[184:187], s[8:9]
	v_pk_mul_f32 v[52:53], v[52:53], v[176:177]
	v_pk_mul_f32 v[54:55], v[54:55], v[178:179]
	v_pk_mul_f32 v[48:49], v[48:49], v[180:181]
	v_pk_mul_f32 v[50:51], v[50:51], v[182:183]
	v_cvt_pk_bf16_f32 v188, v52, v53
	v_cvt_pk_bf16_f32 v189, v54, v55
	v_cvt_pk_bf16_f32 v190, v48, v49
	v_cvt_pk_bf16_f32 v191, v50, v51
	global_store_dwordx4 v156, v[188:191], s[8:9] offset:256
	v_add_u32_e32 v156, 0x200000, v156
	v_pk_mul_f32 v[108:109], v[108:109], v[168:169]
	v_pk_mul_f32 v[110:111], v[110:111], v[170:171]
	v_pk_mul_f32 v[104:105], v[104:105], v[172:173]
	v_pk_mul_f32 v[106:107], v[106:107], v[174:175]
	v_cvt_pk_bf16_f32 v184, v108, v109
	v_cvt_pk_bf16_f32 v185, v110, v111
	v_cvt_pk_bf16_f32 v186, v104, v105
	v_cvt_pk_bf16_f32 v187, v106, v107
	global_store_dwordx4 v156, v[184:187], s[8:9]
	v_pk_mul_f32 v[44:45], v[44:45], v[176:177]
	v_pk_mul_f32 v[46:47], v[46:47], v[178:179]
	v_pk_mul_f32 v[40:41], v[40:41], v[180:181]
	v_pk_mul_f32 v[42:43], v[42:43], v[182:183]
	v_cvt_pk_bf16_f32 v188, v44, v45
	v_cvt_pk_bf16_f32 v189, v46, v47
	v_cvt_pk_bf16_f32 v190, v40, v41
	v_cvt_pk_bf16_f32 v191, v42, v43
	global_store_dwordx4 v156, v[188:191], s[8:9] offset:256
	v_add_u32_e32 v156, 0x200000, v156
	v_pk_mul_f32 v[100:101], v[100:101], v[168:169]
	v_pk_mul_f32 v[102:103], v[102:103], v[170:171]
	v_pk_mul_f32 v[96:97], v[96:97], v[172:173]
	v_pk_mul_f32 v[98:99], v[98:99], v[174:175]
	v_cvt_pk_bf16_f32 v184, v100, v101
	v_cvt_pk_bf16_f32 v185, v102, v103
	v_cvt_pk_bf16_f32 v186, v96, v97
	v_cvt_pk_bf16_f32 v187, v98, v99
	global_store_dwordx4 v156, v[184:187], s[8:9]
	v_pk_mul_f32 v[36:37], v[36:37], v[176:177]
	v_pk_mul_f32 v[38:39], v[38:39], v[178:179]
	v_pk_mul_f32 v[32:33], v[32:33], v[180:181]
	v_pk_mul_f32 v[34:35], v[34:35], v[182:183]
	v_cvt_pk_bf16_f32 v188, v36, v37
	v_cvt_pk_bf16_f32 v189, v38, v39
	v_cvt_pk_bf16_f32 v190, v32, v33
	v_cvt_pk_bf16_f32 v191, v34, v35
	global_store_dwordx4 v156, v[188:191], s[8:9] offset:256
	v_add_u32_e32 v156, 0xa00000, v156
	v_pk_mul_f32 v[92:93], v[92:93], v[168:169]
	v_pk_mul_f32 v[94:95], v[94:95], v[170:171]
	v_pk_mul_f32 v[88:89], v[88:89], v[172:173]
	v_pk_mul_f32 v[90:91], v[90:91], v[174:175]
	v_cvt_pk_bf16_f32 v184, v92, v93
	v_cvt_pk_bf16_f32 v185, v94, v95
	v_cvt_pk_bf16_f32 v186, v88, v89
	v_cvt_pk_bf16_f32 v187, v90, v91
	global_store_dwordx4 v156, v[184:187], s[8:9]
	v_pk_mul_f32 v[28:29], v[28:29], v[176:177]
	v_pk_mul_f32 v[30:31], v[30:31], v[178:179]
	v_pk_mul_f32 v[24:25], v[24:25], v[180:181]
	v_pk_mul_f32 v[26:27], v[26:27], v[182:183]
	v_cvt_pk_bf16_f32 v188, v28, v29
	v_cvt_pk_bf16_f32 v189, v30, v31
	v_cvt_pk_bf16_f32 v190, v24, v25
	v_cvt_pk_bf16_f32 v191, v26, v27
	global_store_dwordx4 v156, v[188:191], s[8:9] offset:256
	v_add_u32_e32 v156, 0x200000, v156
	v_pk_mul_f32 v[84:85], v[84:85], v[168:169]
	v_pk_mul_f32 v[86:87], v[86:87], v[170:171]
	v_pk_mul_f32 v[80:81], v[80:81], v[172:173]
	v_pk_mul_f32 v[82:83], v[82:83], v[174:175]
	v_cvt_pk_bf16_f32 v184, v84, v85
	v_cvt_pk_bf16_f32 v185, v86, v87
	v_cvt_pk_bf16_f32 v186, v80, v81
	v_cvt_pk_bf16_f32 v187, v82, v83
	global_store_dwordx4 v156, v[184:187], s[8:9]
	v_pk_mul_f32 v[20:21], v[20:21], v[176:177]
	v_pk_mul_f32 v[22:23], v[22:23], v[178:179]
	v_pk_mul_f32 v[16:17], v[16:17], v[180:181]
	v_pk_mul_f32 v[18:19], v[18:19], v[182:183]
	v_cvt_pk_bf16_f32 v188, v20, v21
	v_cvt_pk_bf16_f32 v189, v22, v23
	v_cvt_pk_bf16_f32 v190, v16, v17
	v_cvt_pk_bf16_f32 v191, v18, v19
	global_store_dwordx4 v156, v[188:191], s[8:9] offset:256
	v_add_u32_e32 v156, 0x200000, v156
	v_pk_mul_f32 v[76:77], v[76:77], v[168:169]
	v_pk_mul_f32 v[78:79], v[78:79], v[170:171]
	v_pk_mul_f32 v[72:73], v[72:73], v[172:173]
	v_pk_mul_f32 v[74:75], v[74:75], v[174:175]
	v_cvt_pk_bf16_f32 v184, v76, v77
	v_cvt_pk_bf16_f32 v185, v78, v79
	v_cvt_pk_bf16_f32 v186, v72, v73
	v_cvt_pk_bf16_f32 v187, v74, v75
	global_store_dwordx4 v156, v[184:187], s[8:9]
	v_pk_mul_f32 v[12:13], v[12:13], v[176:177]
	v_pk_mul_f32 v[14:15], v[14:15], v[178:179]
	v_pk_mul_f32 v[8:9], v[8:9], v[180:181]
	v_pk_mul_f32 v[10:11], v[10:11], v[182:183]
	v_cvt_pk_bf16_f32 v188, v12, v13
	v_cvt_pk_bf16_f32 v189, v14, v15
	v_cvt_pk_bf16_f32 v190, v8, v9
	v_cvt_pk_bf16_f32 v191, v10, v11
	global_store_dwordx4 v156, v[188:191], s[8:9] offset:256
	v_add_u32_e32 v156, 0x200000, v156
	v_pk_mul_f32 v[68:69], v[68:69], v[168:169]
	v_pk_mul_f32 v[70:71], v[70:71], v[170:171]
	v_pk_mul_f32 v[64:65], v[64:65], v[172:173]
	v_pk_mul_f32 v[66:67], v[66:67], v[174:175]
	v_cvt_pk_bf16_f32 v184, v68, v69
	v_cvt_pk_bf16_f32 v185, v70, v71
	v_cvt_pk_bf16_f32 v186, v64, v65
	v_cvt_pk_bf16_f32 v187, v66, v67
	global_store_dwordx4 v156, v[184:187], s[8:9]
	v_pk_mul_f32 v[4:5], v[4:5], v[176:177]
	v_pk_mul_f32 v[6:7], v[6:7], v[178:179]
	v_pk_mul_f32 v[0:1], v[0:1], v[180:181]
	v_pk_mul_f32 v[2:3], v[2:3], v[182:183]
	v_cvt_pk_bf16_f32 v188, v4, v5
	v_cvt_pk_bf16_f32 v189, v6, v7
	v_cvt_pk_bf16_f32 v190, v0, v1
	v_cvt_pk_bf16_f32 v191, v2, v3
	global_store_dwordx4 v156, v[188:191], s[8:9] offset:256
	s_mov_b64 s[6:7], s[22:23]
	s_and_b64 vcc, exec, s[4:5]
	s_cbranch_vccz .LBB0_707
	s_waitcnt vmcnt(0)
	s_cmpk_gt_u32 s30, 0xff
	s_cbranch_scc1 .LBB0_718
	s_barrier
